# UP epilogue: the last row block no longer writes its two raw rows to the LDS exchange area (only the next tile needs them, via halo)
# baseline (speedup 1.0000x reference)
.LBB0_560:
	s_mov_b32 s98, 1.0
	s_mov_b32 s99, 1.0
	s_mov_b32 s100, 0xbfb8aa3b
	s_mov_b32 s101, 0xbfb8aa3b
	v_readfirstlane_b32 s50, v170
	v_and_b32_e32 v224, 15, v170
	v_bfe_u32 v245, v170, 4, 2
	s_lshr_b32 s50, s50, 6
	s_and_b32 s51, s50, 3
	s_lshr_b32 s50, s50, 2
	s_lshl_b32 s51, s51, 7
	v_lshl_add_u32 v225, v245, 5, s51
	s_bitcmp1_b32 s29, 0
	s_cselect_b32 s3, 0x1800, 0
	s_add_i32 s3, s3, 0x22100
	v_add_u32_e32 v226, s3, v225
	s_lshl_b32 s51, s50, 8
	s_add_i32 s51, s51, s3
	v_lshl_add_u32 v245, v224, 4, s51
	ds_read_b128 v[146:149], v245 offset:4096
	ds_read_b128 v[150:153], v245 offset:4608
	ds_read_b128 v[154:157], v226 offset:5120
	ds_read_b128 v[158:161], v226 offset:5136
	ds_read_b128 v[162:165], v226 offset:5632
	ds_read_b128 v[166:169], v226 offset:5648
	ds_read_b128 v[194:197], v226 offset:512
	ds_read_b128 v[198:201], v226 offset:1536
	ds_read_b128 v[202:205], v226 offset:2560
	ds_read_b128 v[206:209], v226 offset:3584
	s_lshl_b32 s51, s50, 11
	s_add_i32 s51, s51, 0x1f800
	v_add_u32_e32 v227, s51, v225
	s_mul_i32 s51, s28, 0xb000
	s_lshl_b32 s3, s46, 9
	s_add_i32 s51, s51, s3
	v_add_u32_e32 v228, s51, v225
	v_add_u32_e32 v229, 0x2c00, v228
	v_add_u32_e32 v230, 0x5800, v228
	v_add_u32_e32 v231, 0x8400, v228
	s_lshl_b32 s51, s28, 8
	s_lshl_b32 s3, s50, 6
	s_add_i32 s51, s51, s3
	v_lshl_add_u32 v244, v224, 2, s51
	v_mul_u32_u24_e32 v244, 0x1600, v244
	s_lshl_b32 s3, s46, 8
	v_lshrrev_b32_e32 v245, 1, v225
	v_add3_u32 v244, v244, v245, s3
	v_mov_b32_e32 v245, 0x358637bd
	s_waitcnt lgkmcnt(8)
	v_fmamk_f32 v146, v146, 0x3a800000, v245
	v_fmamk_f32 v147, v147, 0x3a800000, v245
	v_fmamk_f32 v148, v148, 0x3a800000, v245
	v_fmamk_f32 v149, v149, 0x3a800000, v245
	v_fmamk_f32 v150, v150, 0x3a800000, v245
	v_fmamk_f32 v151, v151, 0x3a800000, v245
	v_fmamk_f32 v152, v152, 0x3a800000, v245
	v_fmamk_f32 v153, v153, 0x3a800000, v245
	v_rsq_f32_e32 v146, v146
	v_rsq_f32_e32 v147, v147
	v_rsq_f32_e32 v148, v148
	v_rsq_f32_e32 v149, v149
	v_rsq_f32_e32 v150, v150
	v_rsq_f32_e32 v151, v151
	v_rsq_f32_e32 v152, v152
	v_rsq_f32_e32 v153, v153
	s_waitcnt lgkmcnt(4)
	v_pk_fma_f32 v[62:63], v[62:63], v[146:147], v[154:155] op_sel:[0,0,0] op_sel_hi:[1,0,1]
	v_pk_fma_f32 v[64:65], v[64:65], v[146:147], v[156:157] op_sel:[0,0,0] op_sel_hi:[1,0,1]
	v_pk_fma_f32 v[42:43], v[42:43], v[146:147], v[158:159] op_sel:[0,0,0] op_sel_hi:[1,0,1]
	v_pk_fma_f32 v[44:45], v[44:45], v[146:147], v[160:161] op_sel:[0,0,0] op_sel_hi:[1,0,1]
	v_pk_fma_f32 v[134:135], v[134:135], v[146:147], v[162:163] op_sel:[0,0,0] op_sel_hi:[1,0,1]
	v_pk_fma_f32 v[136:137], v[136:137], v[146:147], v[164:165] op_sel:[0,0,0] op_sel_hi:[1,0,1]
	v_pk_fma_f32 v[74:75], v[74:75], v[146:147], v[166:167] op_sel:[0,0,0] op_sel_hi:[1,0,1]
	v_pk_fma_f32 v[76:77], v[76:77], v[146:147], v[168:169] op_sel:[0,0,0] op_sel_hi:[1,0,1]
	v_pk_fma_f32 v[50:51], v[50:51], v[146:147], v[154:155] op_sel:[0,1,0] op_sel_hi:[1,1,1]
	v_pk_fma_f32 v[52:53], v[52:53], v[146:147], v[156:157] op_sel:[0,1,0] op_sel_hi:[1,1,1]
	v_pk_fma_f32 v[38:39], v[38:39], v[146:147], v[158:159] op_sel:[0,1,0] op_sel_hi:[1,1,1]
	v_pk_fma_f32 v[40:41], v[40:41], v[146:147], v[160:161] op_sel:[0,1,0] op_sel_hi:[1,1,1]
	v_pk_fma_f32 v[130:131], v[130:131], v[146:147], v[162:163] op_sel:[0,1,0] op_sel_hi:[1,1,1]
	v_pk_fma_f32 v[132:133], v[132:133], v[146:147], v[164:165] op_sel:[0,1,0] op_sel_hi:[1,1,1]
	v_pk_fma_f32 v[70:71], v[70:71], v[146:147], v[166:167] op_sel:[0,1,0] op_sel_hi:[1,1,1]
	v_pk_fma_f32 v[72:73], v[72:73], v[146:147], v[168:169] op_sel:[0,1,0] op_sel_hi:[1,1,1]
	v_pk_fma_f32 v[46:47], v[46:47], v[148:149], v[154:155] op_sel:[0,0,0] op_sel_hi:[1,0,1]
	v_pk_fma_f32 v[48:49], v[48:49], v[148:149], v[156:157] op_sel:[0,0,0] op_sel_hi:[1,0,1]
	v_pk_fma_f32 v[34:35], v[34:35], v[148:149], v[158:159] op_sel:[0,0,0] op_sel_hi:[1,0,1]
	v_pk_fma_f32 v[36:37], v[36:37], v[148:149], v[160:161] op_sel:[0,0,0] op_sel_hi:[1,0,1]
	v_pk_fma_f32 v[78:79], v[78:79], v[148:149], v[162:163] op_sel:[0,0,0] op_sel_hi:[1,0,1]
	v_pk_fma_f32 v[80:81], v[80:81], v[148:149], v[164:165] op_sel:[0,0,0] op_sel_hi:[1,0,1]
	v_pk_fma_f32 v[66:67], v[66:67], v[148:149], v[166:167] op_sel:[0,0,0] op_sel_hi:[1,0,1]
	v_pk_fma_f32 v[68:69], v[68:69], v[148:149], v[168:169] op_sel:[0,0,0] op_sel_hi:[1,0,1]
	v_pk_fma_f32 v[142:143], v[142:143], v[148:149], v[154:155] op_sel:[0,1,0] op_sel_hi:[1,1,1]
	v_pk_fma_f32 v[144:145], v[144:145], v[148:149], v[156:157] op_sel:[0,1,0] op_sel_hi:[1,1,1]
	v_pk_fma_f32 v[82:83], v[82:83], v[148:149], v[158:159] op_sel:[0,1,0] op_sel_hi:[1,1,1]
	v_pk_fma_f32 v[84:85], v[84:85], v[148:149], v[160:161] op_sel:[0,1,0] op_sel_hi:[1,1,1]
	v_pk_fma_f32 v[138:139], v[138:139], v[148:149], v[162:163] op_sel:[0,1,0] op_sel_hi:[1,1,1]
	v_pk_fma_f32 v[140:141], v[140:141], v[148:149], v[164:165] op_sel:[0,1,0] op_sel_hi:[1,1,1]
	v_pk_fma_f32 v[98:99], v[98:99], v[148:149], v[166:167] op_sel:[0,1,0] op_sel_hi:[1,1,1]
	v_pk_fma_f32 v[100:101], v[100:101], v[148:149], v[168:169] op_sel:[0,1,0] op_sel_hi:[1,1,1]
	v_pk_fma_f32 v[94:95], v[94:95], v[150:151], v[154:155] op_sel:[0,0,0] op_sel_hi:[1,0,1]
	v_pk_fma_f32 v[96:97], v[96:97], v[150:151], v[156:157] op_sel:[0,0,0] op_sel_hi:[1,0,1]
	v_pk_fma_f32 v[10:11], v[10:11], v[150:151], v[158:159] op_sel:[0,0,0] op_sel_hi:[1,0,1]
	v_pk_fma_f32 v[12:13], v[12:13], v[150:151], v[160:161] op_sel:[0,0,0] op_sel_hi:[1,0,1]
	v_pk_fma_f32 v[110:111], v[110:111], v[150:151], v[162:163] op_sel:[0,0,0] op_sel_hi:[1,0,1]
	v_pk_fma_f32 v[112:113], v[112:113], v[150:151], v[164:165] op_sel:[0,0,0] op_sel_hi:[1,0,1]
	v_pk_fma_f32 v[22:23], v[22:23], v[150:151], v[166:167] op_sel:[0,0,0] op_sel_hi:[1,0,1]
	v_pk_fma_f32 v[24:25], v[24:25], v[150:151], v[168:169] op_sel:[0,0,0] op_sel_hi:[1,0,1]
	v_pk_fma_f32 v[90:91], v[90:91], v[150:151], v[154:155] op_sel:[0,1,0] op_sel_hi:[1,1,1]
	v_pk_fma_f32 v[92:93], v[92:93], v[150:151], v[156:157] op_sel:[0,1,0] op_sel_hi:[1,1,1]
	v_pk_fma_f32 v[6:7], v[6:7], v[150:151], v[158:159] op_sel:[0,1,0] op_sel_hi:[1,1,1]
	v_pk_fma_f32 v[8:9], v[8:9], v[150:151], v[160:161] op_sel:[0,1,0] op_sel_hi:[1,1,1]
	v_pk_fma_f32 v[106:107], v[106:107], v[150:151], v[162:163] op_sel:[0,1,0] op_sel_hi:[1,1,1]
	v_pk_fma_f32 v[108:109], v[108:109], v[150:151], v[164:165] op_sel:[0,1,0] op_sel_hi:[1,1,1]
	v_pk_fma_f32 v[18:19], v[18:19], v[150:151], v[166:167] op_sel:[0,1,0] op_sel_hi:[1,1,1]
	v_pk_fma_f32 v[20:21], v[20:21], v[150:151], v[168:169] op_sel:[0,1,0] op_sel_hi:[1,1,1]
	v_pk_fma_f32 v[86:87], v[86:87], v[152:153], v[154:155] op_sel:[0,0,0] op_sel_hi:[1,0,1]
	v_pk_fma_f32 v[88:89], v[88:89], v[152:153], v[156:157] op_sel:[0,0,0] op_sel_hi:[1,0,1]
	v_pk_fma_f32 v[2:3], v[2:3], v[152:153], v[158:159] op_sel:[0,0,0] op_sel_hi:[1,0,1]
	v_pk_fma_f32 v[4:5], v[4:5], v[152:153], v[160:161] op_sel:[0,0,0] op_sel_hi:[1,0,1]
	v_pk_fma_f32 v[102:103], v[102:103], v[152:153], v[162:163] op_sel:[0,0,0] op_sel_hi:[1,0,1]
	v_pk_fma_f32 v[104:105], v[104:105], v[152:153], v[164:165] op_sel:[0,0,0] op_sel_hi:[1,0,1]
	v_pk_fma_f32 v[14:15], v[14:15], v[152:153], v[166:167] op_sel:[0,0,0] op_sel_hi:[1,0,1]
	v_pk_fma_f32 v[16:17], v[16:17], v[152:153], v[168:169] op_sel:[0,0,0] op_sel_hi:[1,0,1]
	v_pk_fma_f32 v[114:115], v[114:115], v[152:153], v[154:155] op_sel:[0,1,0] op_sel_hi:[1,1,1]
	v_pk_fma_f32 v[116:117], v[116:117], v[152:153], v[156:157] op_sel:[0,1,0] op_sel_hi:[1,1,1]
	v_pk_fma_f32 v[26:27], v[26:27], v[152:153], v[158:159] op_sel:[0,1,0] op_sel_hi:[1,1,1]
	v_pk_fma_f32 v[28:29], v[28:29], v[152:153], v[160:161] op_sel:[0,1,0] op_sel_hi:[1,1,1]
	v_pk_fma_f32 v[126:127], v[126:127], v[152:153], v[162:163] op_sel:[0,1,0] op_sel_hi:[1,1,1]
	v_pk_fma_f32 v[128:129], v[128:129], v[152:153], v[164:165] op_sel:[0,1,0] op_sel_hi:[1,1,1]
	v_pk_fma_f32 v[58:59], v[58:59], v[152:153], v[166:167] op_sel:[0,1,0] op_sel_hi:[1,1,1]
	v_pk_fma_f32 v[60:61], v[60:61], v[152:153], v[168:169] op_sel:[0,1,0] op_sel_hi:[1,1,1]
	v_cmp_eq_u32_e32 vcc, 15, v224
	s_and_saveexec_b64 s[8:9], vcc
	ds_write_b128 v227, v[46:49] offset:2048
	ds_write_b128 v227, v[34:37] offset:2064
	ds_write_b128 v227, v[78:81] offset:2560
	ds_write_b128 v227, v[66:69] offset:2576
	ds_write_b128 v227, v[142:145] offset:3072
	ds_write_b128 v227, v[82:85] offset:3088
	ds_write_b128 v227, v[138:141] offset:3584
	ds_write_b128 v227, v[98:101] offset:3600
	s_cmp_lg_u32 s50, 1
	s_cbranch_scc0 .Lnepia_halo
	ds_write_b128 v227, v[86:89] offset:6144
	ds_write_b128 v227, v[2:5] offset:6160
	ds_write_b128 v227, v[102:105] offset:6656
	ds_write_b128 v227, v[14:17] offset:6672
	ds_write_b128 v227, v[114:117] offset:7168
	ds_write_b128 v227, v[26:29] offset:7184
	ds_write_b128 v227, v[126:129] offset:7680
	ds_write_b128 v227, v[58:61] offset:7696
	s_branch .Lnepia_nohalo
.Lnepia_halo:
	s_add_u32 s48, s88, 0x2a00000
	s_addc_u32 s49, s89, 0
	global_store_dwordx4 v228, v[86:89], s[48:49] offset:0
	global_store_dwordx4 v228, v[2:5], s[48:49] offset:16
	global_store_dwordx4 v229, v[102:105], s[48:49] offset:0
	global_store_dwordx4 v229, v[14:17], s[48:49] offset:16
	global_store_dwordx4 v230, v[114:117], s[48:49] offset:0
	global_store_dwordx4 v230, v[26:29], s[48:49] offset:16
	global_store_dwordx4 v231, v[126:129], s[48:49] offset:0
	global_store_dwordx4 v231, v[58:61], s[48:49] offset:16

.LBB0_1320:
	s_mov_b32 s98, 1.0
	s_mov_b32 s99, 1.0
	s_mov_b32 s100, 0xbfb8aa3b
	s_mov_b32 s101, 0xbfb8aa3b
	v_readfirstlane_b32 s54, v170
	v_and_b32_e32 v224, 15, v170
	v_bfe_u32 v245, v170, 4, 2
	s_lshr_b32 s54, s54, 6
	s_and_b32 s55, s54, 3
	s_lshr_b32 s54, s54, 2
	s_lshl_b32 s55, s55, 7
	v_lshl_add_u32 v225, v245, 5, s55
	s_bitcmp1_b32 s31, 0
	s_cselect_b32 s51, 0x1800, 0
	s_add_i32 s51, s51, 0x22100
	v_add_u32_e32 v226, s51, v225
	s_lshl_b32 s55, s54, 8
	s_add_i32 s55, s55, s51
	v_lshl_add_u32 v245, v224, 4, s55
	ds_read_b128 v[146:149], v245 offset:4096
	ds_read_b128 v[150:153], v245 offset:4608
	ds_read_b128 v[154:157], v226 offset:5120
	ds_read_b128 v[158:161], v226 offset:5136
	ds_read_b128 v[162:165], v226 offset:5632
	ds_read_b128 v[166:169], v226 offset:5648
	ds_read_b128 v[196:199], v226 offset:512
	ds_read_b128 v[200:203], v226 offset:1536
	ds_read_b128 v[204:207], v226 offset:2560
	ds_read_b128 v[208:211], v226 offset:3584
	s_lshl_b32 s55, s54, 11
	s_add_i32 s55, s55, 0x1f800
	v_add_u32_e32 v227, s55, v225
	s_mul_i32 s55, s30, 0xb000
	s_lshl_b32 s51, s50, 9
	s_add_i32 s55, s55, s51
	v_add_u32_e32 v228, s55, v225
	v_add_u32_e32 v229, 0x2c00, v228
	v_add_u32_e32 v230, 0x5800, v228
	v_add_u32_e32 v231, 0x8400, v228
	s_lshl_b32 s55, s30, 8
	s_lshl_b32 s51, s54, 6
	s_add_i32 s55, s55, s51
	v_lshl_add_u32 v244, v224, 2, s55
	v_mul_u32_u24_e32 v244, 0x1600, v244
	s_lshl_b32 s51, s50, 8
	v_lshrrev_b32_e32 v245, 1, v225
	v_add3_u32 v244, v244, v245, s51
	v_mov_b32_e32 v245, 0x358637bd
	s_waitcnt lgkmcnt(8)
	v_fmamk_f32 v146, v146, 0x3a800000, v245
	v_fmamk_f32 v147, v147, 0x3a800000, v245
	v_fmamk_f32 v148, v148, 0x3a800000, v245
	v_fmamk_f32 v149, v149, 0x3a800000, v245
	v_fmamk_f32 v150, v150, 0x3a800000, v245
	v_fmamk_f32 v151, v151, 0x3a800000, v245
	v_fmamk_f32 v152, v152, 0x3a800000, v245
	v_fmamk_f32 v153, v153, 0x3a800000, v245
	v_rsq_f32_e32 v146, v146
	v_rsq_f32_e32 v147, v147
	v_rsq_f32_e32 v148, v148
	v_rsq_f32_e32 v149, v149
	v_rsq_f32_e32 v150, v150
	v_rsq_f32_e32 v151, v151
	v_rsq_f32_e32 v152, v152
	v_rsq_f32_e32 v153, v153
	s_waitcnt lgkmcnt(4)
	v_pk_fma_f32 v[62:63], v[62:63], v[146:147], v[154:155] op_sel:[0,0,0] op_sel_hi:[1,0,1]
	v_pk_fma_f32 v[64:65], v[64:65], v[146:147], v[156:157] op_sel:[0,0,0] op_sel_hi:[1,0,1]
	v_pk_fma_f32 v[42:43], v[42:43], v[146:147], v[158:159] op_sel:[0,0,0] op_sel_hi:[1,0,1]
	v_pk_fma_f32 v[44:45], v[44:45], v[146:147], v[160:161] op_sel:[0,0,0] op_sel_hi:[1,0,1]
	v_pk_fma_f32 v[134:135], v[134:135], v[146:147], v[162:163] op_sel:[0,0,0] op_sel_hi:[1,0,1]
	v_pk_fma_f32 v[136:137], v[136:137], v[146:147], v[164:165] op_sel:[0,0,0] op_sel_hi:[1,0,1]
	v_pk_fma_f32 v[74:75], v[74:75], v[146:147], v[166:167] op_sel:[0,0,0] op_sel_hi:[1,0,1]
	v_pk_fma_f32 v[76:77], v[76:77], v[146:147], v[168:169] op_sel:[0,0,0] op_sel_hi:[1,0,1]
	v_pk_fma_f32 v[50:51], v[50:51], v[146:147], v[154:155] op_sel:[0,1,0] op_sel_hi:[1,1,1]
	v_pk_fma_f32 v[52:53], v[52:53], v[146:147], v[156:157] op_sel:[0,1,0] op_sel_hi:[1,1,1]
	v_pk_fma_f32 v[38:39], v[38:39], v[146:147], v[158:159] op_sel:[0,1,0] op_sel_hi:[1,1,1]
	v_pk_fma_f32 v[40:41], v[40:41], v[146:147], v[160:161] op_sel:[0,1,0] op_sel_hi:[1,1,1]
	v_pk_fma_f32 v[130:131], v[130:131], v[146:147], v[162:163] op_sel:[0,1,0] op_sel_hi:[1,1,1]
	v_pk_fma_f32 v[132:133], v[132:133], v[146:147], v[164:165] op_sel:[0,1,0] op_sel_hi:[1,1,1]
	v_pk_fma_f32 v[70:71], v[70:71], v[146:147], v[166:167] op_sel:[0,1,0] op_sel_hi:[1,1,1]
	v_pk_fma_f32 v[72:73], v[72:73], v[146:147], v[168:169] op_sel:[0,1,0] op_sel_hi:[1,1,1]
	v_pk_fma_f32 v[46:47], v[46:47], v[148:149], v[154:155] op_sel:[0,0,0] op_sel_hi:[1,0,1]
	v_pk_fma_f32 v[48:49], v[48:49], v[148:149], v[156:157] op_sel:[0,0,0] op_sel_hi:[1,0,1]
	v_pk_fma_f32 v[34:35], v[34:35], v[148:149], v[158:159] op_sel:[0,0,0] op_sel_hi:[1,0,1]
	v_pk_fma_f32 v[36:37], v[36:37], v[148:149], v[160:161] op_sel:[0,0,0] op_sel_hi:[1,0,1]
	v_pk_fma_f32 v[78:79], v[78:79], v[148:149], v[162:163] op_sel:[0,0,0] op_sel_hi:[1,0,1]
	v_pk_fma_f32 v[80:81], v[80:81], v[148:149], v[164:165] op_sel:[0,0,0] op_sel_hi:[1,0,1]
	v_pk_fma_f32 v[66:67], v[66:67], v[148:149], v[166:167] op_sel:[0,0,0] op_sel_hi:[1,0,1]
	v_pk_fma_f32 v[68:69], v[68:69], v[148:149], v[168:169] op_sel:[0,0,0] op_sel_hi:[1,0,1]
	v_pk_fma_f32 v[142:143], v[142:143], v[148:149], v[154:155] op_sel:[0,1,0] op_sel_hi:[1,1,1]
	v_pk_fma_f32 v[144:145], v[144:145], v[148:149], v[156:157] op_sel:[0,1,0] op_sel_hi:[1,1,1]
	v_pk_fma_f32 v[82:83], v[82:83], v[148:149], v[158:159] op_sel:[0,1,0] op_sel_hi:[1,1,1]
	v_pk_fma_f32 v[84:85], v[84:85], v[148:149], v[160:161] op_sel:[0,1,0] op_sel_hi:[1,1,1]
	v_pk_fma_f32 v[138:139], v[138:139], v[148:149], v[162:163] op_sel:[0,1,0] op_sel_hi:[1,1,1]
	v_pk_fma_f32 v[140:141], v[140:141], v[148:149], v[164:165] op_sel:[0,1,0] op_sel_hi:[1,1,1]
	v_pk_fma_f32 v[98:99], v[98:99], v[148:149], v[166:167] op_sel:[0,1,0] op_sel_hi:[1,1,1]
	v_pk_fma_f32 v[100:101], v[100:101], v[148:149], v[168:169] op_sel:[0,1,0] op_sel_hi:[1,1,1]
	v_pk_fma_f32 v[94:95], v[94:95], v[150:151], v[154:155] op_sel:[0,0,0] op_sel_hi:[1,0,1]
	v_pk_fma_f32 v[96:97], v[96:97], v[150:151], v[156:157] op_sel:[0,0,0] op_sel_hi:[1,0,1]
	v_pk_fma_f32 v[10:11], v[10:11], v[150:151], v[158:159] op_sel:[0,0,0] op_sel_hi:[1,0,1]
	v_pk_fma_f32 v[12:13], v[12:13], v[150:151], v[160:161] op_sel:[0,0,0] op_sel_hi:[1,0,1]
	v_pk_fma_f32 v[110:111], v[110:111], v[150:151], v[162:163] op_sel:[0,0,0] op_sel_hi:[1,0,1]
	v_pk_fma_f32 v[112:113], v[112:113], v[150:151], v[164:165] op_sel:[0,0,0] op_sel_hi:[1,0,1]
	v_pk_fma_f32 v[22:23], v[22:23], v[150:151], v[166:167] op_sel:[0,0,0] op_sel_hi:[1,0,1]
	v_pk_fma_f32 v[24:25], v[24:25], v[150:151], v[168:169] op_sel:[0,0,0] op_sel_hi:[1,0,1]
	v_pk_fma_f32 v[90:91], v[90:91], v[150:151], v[154:155] op_sel:[0,1,0] op_sel_hi:[1,1,1]
	v_pk_fma_f32 v[92:93], v[92:93], v[150:151], v[156:157] op_sel:[0,1,0] op_sel_hi:[1,1,1]
	v_pk_fma_f32 v[6:7], v[6:7], v[150:151], v[158:159] op_sel:[0,1,0] op_sel_hi:[1,1,1]
	v_pk_fma_f32 v[8:9], v[8:9], v[150:151], v[160:161] op_sel:[0,1,0] op_sel_hi:[1,1,1]
	v_pk_fma_f32 v[106:107], v[106:107], v[150:151], v[162:163] op_sel:[0,1,0] op_sel_hi:[1,1,1]
	v_pk_fma_f32 v[108:109], v[108:109], v[150:151], v[164:165] op_sel:[0,1,0] op_sel_hi:[1,1,1]
	v_pk_fma_f32 v[18:19], v[18:19], v[150:151], v[166:167] op_sel:[0,1,0] op_sel_hi:[1,1,1]
	v_pk_fma_f32 v[20:21], v[20:21], v[150:151], v[168:169] op_sel:[0,1,0] op_sel_hi:[1,1,1]
	v_pk_fma_f32 v[86:87], v[86:87], v[152:153], v[154:155] op_sel:[0,0,0] op_sel_hi:[1,0,1]
	v_pk_fma_f32 v[88:89], v[88:89], v[152:153], v[156:157] op_sel:[0,0,0] op_sel_hi:[1,0,1]
	v_pk_fma_f32 v[2:3], v[2:3], v[152:153], v[158:159] op_sel:[0,0,0] op_sel_hi:[1,0,1]
	v_pk_fma_f32 v[4:5], v[4:5], v[152:153], v[160:161] op_sel:[0,0,0] op_sel_hi:[1,0,1]
	v_pk_fma_f32 v[102:103], v[102:103], v[152:153], v[162:163] op_sel:[0,0,0] op_sel_hi:[1,0,1]
	v_pk_fma_f32 v[104:105], v[104:105], v[152:153], v[164:165] op_sel:[0,0,0] op_sel_hi:[1,0,1]
	v_pk_fma_f32 v[14:15], v[14:15], v[152:153], v[166:167] op_sel:[0,0,0] op_sel_hi:[1,0,1]
	v_pk_fma_f32 v[16:17], v[16:17], v[152:153], v[168:169] op_sel:[0,0,0] op_sel_hi:[1,0,1]
	v_pk_fma_f32 v[114:115], v[114:115], v[152:153], v[154:155] op_sel:[0,1,0] op_sel_hi:[1,1,1]
	v_pk_fma_f32 v[116:117], v[116:117], v[152:153], v[156:157] op_sel:[0,1,0] op_sel_hi:[1,1,1]
	v_pk_fma_f32 v[26:27], v[26:27], v[152:153], v[158:159] op_sel:[0,1,0] op_sel_hi:[1,1,1]
	v_pk_fma_f32 v[28:29], v[28:29], v[152:153], v[160:161] op_sel:[0,1,0] op_sel_hi:[1,1,1]
	v_pk_fma_f32 v[126:127], v[126:127], v[152:153], v[162:163] op_sel:[0,1,0] op_sel_hi:[1,1,1]
	v_pk_fma_f32 v[128:129], v[128:129], v[152:153], v[164:165] op_sel:[0,1,0] op_sel_hi:[1,1,1]
	v_pk_fma_f32 v[58:59], v[58:59], v[152:153], v[166:167] op_sel:[0,1,0] op_sel_hi:[1,1,1]
	v_pk_fma_f32 v[60:61], v[60:61], v[152:153], v[168:169] op_sel:[0,1,0] op_sel_hi:[1,1,1]
	v_cmp_eq_u32_e32 vcc, 15, v224
	s_and_saveexec_b64 s[8:9], vcc
	ds_write_b128 v227, v[46:49] offset:2048
	ds_write_b128 v227, v[34:37] offset:2064
	ds_write_b128 v227, v[78:81] offset:2560
	ds_write_b128 v227, v[66:69] offset:2576
	ds_write_b128 v227, v[142:145] offset:3072
	ds_write_b128 v227, v[82:85] offset:3088
	ds_write_b128 v227, v[138:141] offset:3584
	ds_write_b128 v227, v[98:101] offset:3600
	s_cmp_lg_u32 s54, 1
	s_cbranch_scc0 .Lnepib_halo
	ds_write_b128 v227, v[86:89] offset:6144
	ds_write_b128 v227, v[2:5] offset:6160
	ds_write_b128 v227, v[102:105] offset:6656
	ds_write_b128 v227, v[14:17] offset:6672
	ds_write_b128 v227, v[114:117] offset:7168
	ds_write_b128 v227, v[26:29] offset:7184
	ds_write_b128 v227, v[126:129] offset:7680
	ds_write_b128 v227, v[58:61] offset:7696
	s_branch .Lnepib_nohalo
.Lnepib_halo:
	s_add_u32 s52, s88, 0x2a00000
	s_addc_u32 s53, s89, 0
	global_store_dwordx4 v228, v[86:89], s[52:53] offset:0
	global_store_dwordx4 v228, v[2:5], s[52:53] offset:16
	global_store_dwordx4 v229, v[102:105], s[52:53] offset:0
	global_store_dwordx4 v229, v[14:17], s[52:53] offset:16
	global_store_dwordx4 v230, v[114:117], s[52:53] offset:0
	global_store_dwordx4 v230, v[26:29], s[52:53] offset:16
	global_store_dwordx4 v231, v[126:129], s[52:53] offset:0
	global_store_dwordx4 v231, v[58:61], s[52:53] offset:16
